# speedup vs baseline: 1.0530x; 1.0003x over previous
; #define MFMA16(a, b, c) __builtin_amdgcn_mfma_f32_16x16x32_bf16((a), (b), (c), 0, 0, 0)
; __device__ __forceinline__ bf16x8 gld16(const void* p) { bf16x8 v; asm volatile("global_load_dwordx4 %0, %1, off" : "=v"(v) : "v"(p) : "memory"); return v; }
; template <bool SWAP>
; __device__ __forceinline__ void gemm_big(const bfu* __restrict__ A, int lda, const bfu* __restrict__ B, int ldb, int K,
;                                          f32x4 (&acc)[8][4], bfu* sm, const bfu* An = nullptr, const bfu* Bn = nullptr) {
;     ...
;   auto gl = [&](bf16x8 (&ra)[4], bf16x8 (&rb)[2], int kt) {
;     const bool nx = (kt >= nk);
;     const bfu* pa = nx ? (chain ? Apn + (kt - nk) * 32 : Ap + (nk - 1) * 32) : Ap + kt * 32;
;     const bfu* pb = nx ? (chain ? Bpn + (kt - nk) * 32 : Bp + (nk - 1) * 32) : Bp + kt * 32;
; #pragma unroll
;     for (int q = 0; q < 4; ++q) ra[q] = gld16(pa + (size_t)(64 * q) * lda);
; #pragma unroll
;     for (int q = 0; q < 2; ++q) rb[q] = gld16(pb + (size_t)(64 * q) * ldb);
;   };
;   auto wt = [&](bf16x8 (&ra)[4], bf16x8 (&rb)[2]) {
;     asm volatile("s_waitcnt vmcnt(6)" : "+v"(ra[0]), "+v"(ra[1]), "+v"(ra[2]), "+v"(ra[3]), "+v"(rb[0]), "+v"(rb[1]) : : "memory");
;   };
;   auto st = [&](const bf16x8 (&ra)[4], const bf16x8 (&rb)[2], int buf) {
; #pragma unroll
;     for (int q = 0; q < 4; ++q) *(bf16x8*)(As + (buf * 256 + lrow + 64 * q) * 40 + lch) = ra[q];
; #pragma unroll
;     for (int q = 0; q < 2; ++q) *(bf16x8*)(Bs + (buf * 128 + brow + 64 * q) * 40 + lch) = rb[q];
;   };
;   auto comp = [&](int buf, auto&& mid) {
;     const bfu* as = As + buf * 256 * 40 + (wr * 128 + c15) * 40 + g * 8;
;     const bfu* bs = Bs + buf * 128 * 40 + (wc * 64 + c15) * 40 + g * 8;
;     bf16x8 b[4];
; #pragma unroll
;     for (int j = 0; j < 4; ++j) b[j] = *(const bf16x8*)(bs + j * 16 * 40);
;     {
;       bf16x8 a[4];
; #pragma unroll
;       for (int i = 0; i < 4; ++i) a[i] = *(const bf16x8*)(as + i * 16 * 40);
;       mid();
;       __builtin_amdgcn_s_setprio(1);
; #pragma unroll
;       for (int i = 0; i < 4; ++i)
; #pragma unroll
;         for (int j = 0; j < 4; ++j) acc[i][j] = SWAP ? MFMA16(b[j], a[i], acc[i][j]) : MFMA16(a[i], b[j], acc[i][j]);
;       __builtin_amdgcn_s_setprio(0);
;     }
;     ...
;   for (int kt = 0; kt < nk; kt += 2) {
;     gl(ra0, rb0, kt + 2);
;     comp(0, [&]() { wt(ra1, rb1); st(ra1, rb1, 1); });
;     __syncthreads();
.LBB0_110:
	s_add_i32 s27, s17, 2
	s_cmp_lt_u32 s17, 30
	s_cselect_b64 s[0:1], -1, 0
	s_add_i32 s2, s15, 0x400
	s_and_b64 s[28:29], s[10:11], exec
	s_cselect_b32 s28, 0x3e0, s15
	s_and_b64 vcc, s[0:1], exec
	s_cselect_b32 s2, s2, s28
	v_cndmask_b32_e64 v185, v157, v165, s[0:1]
	v_cndmask_b32_e64 v184, v152, v164, s[0:1]
	v_cndmask_b32_e64 v187, v159, v167, s[0:1]
	v_cndmask_b32_e64 v186, v170, v166, s[0:1]
	s_lshl_b64 s[0:1], s[2:3], 1
	v_lshl_add_u64 v[208:209], v[184:185], 0, s[0:1]
	v_lshl_add_u64 v[216:217], v[186:187], 0, s[0:1]
	ds_read_b128 v[220:223], v199 offset:32768
	ds_read_b128 v[224:227], v199 offset:33792
	ds_read_b128 v[228:231], v199 offset:34816
	ds_read_b128 v[232:235], v199 offset:35840
	ds_read_b128 v[236:239], v172
	ds_read_b128 v[240:243], v172 offset:1024
	ds_read_b128 v[244:247], v172 offset:2048
	ds_read_b128 v[248:251], v172 offset:3072
	s_waitcnt vmcnt(0)
	ds_write_b128 v168, v[128:131] offset:16384
	ds_write_b128 v168, v[132:135] offset:20480
	ds_write_b128 v168, v[136:139] offset:24576
	ds_write_b128 v168, v[140:143] offset:28672
	ds_write_b128 v169, v[144:147] offset:40960
	ds_write_b128 v169, v[148:151] offset:45056
	s_cmp_lt_u32 s17, 29
	s_cselect_b64 s[0:1], -1, 0
	s_add_i32 s2, s15, 0x420
	s_add_i32 s17, s15, 32
	s_and_b64 s[28:29], s[10:11], exec
	s_cselect_b32 s17, 0x3e0, s17
	s_and_b64 s[28:29], s[0:1], exec
	s_cselect_b32 s2, s2, s17
	v_cndmask_b32_e64 v129, v157, v165, s[0:1]
	v_cndmask_b32_e64 v128, v152, v164, s[0:1]
	v_cndmask_b32_e64 v131, v159, v167, s[0:1]
	v_cndmask_b32_e64 v130, v170, v166, s[0:1]
	s_lshl_b64 s[0:1], s[2:3], 1
	v_lshl_add_u64 v[140:141], v[128:129], 0, s[0:1]
	v_lshl_add_u64 v[148:149], v[130:131], 0, s[0:1]
	s_setprio 1
	s_waitcnt lgkmcnt(9)
	v_mfma_f32_16x16x32_bf16 v[124:127], v[220:223], v[236:239], v[124:127]
	global_load_dwordx4 v[184:187], v[208:209], off
	v_mfma_f32_16x16x32_bf16 v[120:123], v[224:227], v[236:239], v[120:123]
	global_load_dwordx4 v[128:131], v[140:141], off
	v_mfma_f32_16x16x32_bf16 v[116:119], v[228:231], v[236:239], v[116:119]
	v_lshl_add_u64 v[200:201], v[208:209], 0, s[8:9]
	global_load_dwordx4 v[200:203], v[200:201], off
	v_mfma_f32_16x16x32_bf16 v[112:115], v[232:235], v[236:239], v[112:115]
	v_lshl_add_u64 v[132:133], v[140:141], 0, s[8:9]
	global_load_dwordx4 v[132:135], v[132:133], off
	s_waitcnt lgkmcnt(8)
	v_mfma_f32_16x16x32_bf16 v[108:111], v[220:223], v[240:243], v[108:111]
	v_lshl_add_u64 v[204:205], v[208:209], 0, s[4:5]
	global_load_dwordx4 v[204:207], v[204:205], off
	v_mfma_f32_16x16x32_bf16 v[104:107], v[224:227], v[240:243], v[104:107]
	v_lshl_add_u64 v[136:137], v[140:141], 0, s[4:5]
	global_load_dwordx4 v[136:139], v[136:137], off
	v_mfma_f32_16x16x32_bf16 v[100:103], v[228:231], v[240:243], v[100:103]
	v_lshl_add_u64 v[208:209], v[208:209], 0, s[90:91]
	global_load_dwordx4 v[208:211], v[208:209], off
	v_mfma_f32_16x16x32_bf16 v[96:99], v[232:235], v[240:243], v[96:99]
	v_lshl_add_u64 v[140:141], v[140:141], 0, s[90:91]
	global_load_dwordx4 v[140:143], v[140:141], off
	s_waitcnt lgkmcnt(7)
	v_mfma_f32_16x16x32_bf16 v[92:95], v[220:223], v[244:247], v[92:95]
	global_load_dwordx4 v[212:215], v[216:217], off
	v_mfma_f32_16x16x32_bf16 v[88:91], v[224:227], v[244:247], v[88:91]
	global_load_dwordx4 v[144:147], v[148:149], off
	v_mfma_f32_16x16x32_bf16 v[84:87], v[228:231], v[244:247], v[84:87]
	v_lshl_add_u64 v[216:217], v[216:217], 0, s[8:9]
	global_load_dwordx4 v[216:219], v[216:217], off
	v_mfma_f32_16x16x32_bf16 v[80:83], v[232:235], v[244:247], v[80:83]
	v_lshl_add_u64 v[148:149], v[148:149], 0, s[8:9]
	global_load_dwordx4 v[148:151], v[148:149], off
	s_waitcnt lgkmcnt(6)
	v_mfma_f32_16x16x32_bf16 v[76:79], v[220:223], v[248:251], v[76:79]
	v_mfma_f32_16x16x32_bf16 v[72:75], v[224:227], v[248:251], v[72:75]
	v_mfma_f32_16x16x32_bf16 v[68:71], v[228:231], v[248:251], v[68:71]
	v_mfma_f32_16x16x32_bf16 v[64:67], v[232:235], v[248:251], v[64:67]
	s_setprio 0
	ds_read_b128 v[236:239], v172 offset:4096
	ds_read_b128 v[240:243], v172 offset:5120
	ds_read_b128 v[244:247], v172 offset:6144
	ds_read_b128 v[248:251], v172 offset:7168
	s_setprio 1
	s_waitcnt lgkmcnt(3)
	v_mfma_f32_16x16x32_bf16 v[60:63], v[220:223], v[236:239], v[60:63]
	v_mfma_f32_16x16x32_bf16 v[56:59], v[224:227], v[236:239], v[56:59]
	v_mfma_f32_16x16x32_bf16 v[52:55], v[228:231], v[236:239], v[52:55]
	v_mfma_f32_16x16x32_bf16 v[48:51], v[232:235], v[236:239], v[48:51]
	s_waitcnt lgkmcnt(2)
	v_mfma_f32_16x16x32_bf16 v[44:47], v[220:223], v[240:243], v[44:47]
	v_mfma_f32_16x16x32_bf16 v[40:43], v[224:227], v[240:243], v[40:43]
	v_mfma_f32_16x16x32_bf16 v[36:39], v[228:231], v[240:243], v[36:39]
	v_mfma_f32_16x16x32_bf16 v[32:35], v[232:235], v[240:243], v[32:35]
	s_waitcnt lgkmcnt(1)
	v_mfma_f32_16x16x32_bf16 v[28:31], v[220:223], v[244:247], v[28:31]
	v_mfma_f32_16x16x32_bf16 v[24:27], v[224:227], v[244:247], v[24:27]
	v_mfma_f32_16x16x32_bf16 v[20:23], v[228:231], v[244:247], v[20:23]
	v_mfma_f32_16x16x32_bf16 v[16:19], v[232:235], v[244:247], v[16:19]
	s_waitcnt lgkmcnt(0)
	v_mfma_f32_16x16x32_bf16 v[12:15], v[220:223], v[248:251], v[12:15]
	v_mfma_f32_16x16x32_bf16 v[8:11], v[224:227], v[248:251], v[8:11]
	v_mfma_f32_16x16x32_bf16 v[4:7], v[228:231], v[248:251], v[4:7]
	v_mfma_f32_16x16x32_bf16 v[0:3], v[232:235], v[248:251], v[0:3]
	s_setprio 0
	s_barrier
; #define MFMA16(a, b, c) __builtin_amdgcn_mfma_f32_16x16x32_bf16((a), (b), (c), 0, 0, 0)
;   __device__ __forceinline__ float* small() const { return (float*)(b + L::o_small); }
; template <bool SWAP>
; __device__ __forceinline__ void gemm_big(const bfu* __restrict__ A, int lda, const bfu* __restrict__ B, int ldb, int K,
;                                          f32x4 (&acc)[8][4], bfu* sm, const bfu* An = nullptr, const bfu* Bn = nullptr) {
;     ...
;     {
;       bf16x8 a[4];
; #pragma unroll
;       for (int i = 0; i < 4; ++i) a[i] = *(const bf16x8*)(as + (i + 4) * 16 * 40);
;       __builtin_amdgcn_s_setprio(1);
; #pragma unroll
;       for (int i = 0; i < 4; ++i)
; #pragma unroll
;         for (int j = 0; j < 4; ++j) acc[i + 4][j] = SWAP ? MFMA16(b[j], a[i], acc[i + 4][j]) : MFMA16(a[i], b[j], acc[i + 4][j]);
;       __builtin_amdgcn_s_setprio(0);
;     }
;   };
; template <int G>
; __device__ __forceinline__ void p1_big(const Params& P, const Ptrs<G>& w, int layer, int mt, int nt, bfu* sm, int mtn, int ntn) {
;     ...
;       if (wc == 0 && g == 0) {
; #pragma unroll
;         for (int i = 0; i < 8; ++i) {
;           float* sp = w.small() + (size_t)(m0 + wr * 128 + 16 * i + c15) * 16;
; #pragma unroll
;           for (int j = 0; j < 4; ++j) *(float4*)(sp + 4 * j) = make_float4(acc[i][j][0], acc[i][j][1], acc[i][j][2], acc[i][j][3]);
;         }
;       }
	ds_read_b128 v[220:223], v199 offset:40960
	ds_read_b128 v[224:227], v199 offset:41984
	ds_read_b128 v[228:231], v199 offset:43008
	ds_read_b128 v[232:235], v199 offset:44032
	ds_read_b128 v[236:239], v172 offset:16384
	ds_read_b128 v[240:243], v172 offset:17408
	ds_read_b128 v[244:247], v172 offset:18432
	ds_read_b128 v[248:251], v172 offset:19456
	s_setprio 1
	s_waitcnt lgkmcnt(3)
	v_mfma_f32_16x16x32_bf16 v[124:127], v[220:223], v[236:239], v[124:127]
	v_mfma_f32_16x16x32_bf16 v[120:123], v[224:227], v[236:239], v[120:123]
	v_mfma_f32_16x16x32_bf16 v[116:119], v[228:231], v[236:239], v[116:119]
	v_mfma_f32_16x16x32_bf16 v[112:115], v[232:235], v[236:239], v[112:115]
	s_waitcnt lgkmcnt(2)
	v_mfma_f32_16x16x32_bf16 v[108:111], v[220:223], v[240:243], v[108:111]
	v_mfma_f32_16x16x32_bf16 v[104:107], v[224:227], v[240:243], v[104:107]
	v_mfma_f32_16x16x32_bf16 v[100:103], v[228:231], v[240:243], v[100:103]
	v_mfma_f32_16x16x32_bf16 v[96:99], v[232:235], v[240:243], v[96:99]
	s_waitcnt lgkmcnt(1)
	v_mfma_f32_16x16x32_bf16 v[92:95], v[220:223], v[244:247], v[92:95]
	v_mfma_f32_16x16x32_bf16 v[88:91], v[224:227], v[244:247], v[88:91]
	v_mfma_f32_16x16x32_bf16 v[84:87], v[228:231], v[244:247], v[84:87]
	v_mfma_f32_16x16x32_bf16 v[80:83], v[232:235], v[244:247], v[80:83]
	s_waitcnt lgkmcnt(0)
	v_mfma_f32_16x16x32_bf16 v[76:79], v[220:223], v[248:251], v[76:79]
	v_mfma_f32_16x16x32_bf16 v[72:75], v[224:227], v[248:251], v[72:75]
	v_mfma_f32_16x16x32_bf16 v[68:71], v[228:231], v[248:251], v[68:71]
	v_mfma_f32_16x16x32_bf16 v[64:67], v[232:235], v[248:251], v[64:67]
	s_setprio 0
	ds_read_b128 v[236:239], v172 offset:20480
	ds_read_b128 v[240:243], v172 offset:21504
	ds_read_b128 v[244:247], v172 offset:22528
	ds_read_b128 v[248:251], v172 offset:23552
	s_setprio 1
	s_waitcnt lgkmcnt(3)
	v_mfma_f32_16x16x32_bf16 v[60:63], v[220:223], v[236:239], v[60:63]
	v_mfma_f32_16x16x32_bf16 v[56:59], v[224:227], v[236:239], v[56:59]
	v_mfma_f32_16x16x32_bf16 v[52:55], v[228:231], v[236:239], v[52:55]
	v_mfma_f32_16x16x32_bf16 v[48:51], v[232:235], v[236:239], v[48:51]
	s_waitcnt lgkmcnt(2)
	v_mfma_f32_16x16x32_bf16 v[44:47], v[220:223], v[240:243], v[44:47]
	v_mfma_f32_16x16x32_bf16 v[40:43], v[224:227], v[240:243], v[40:43]
	v_mfma_f32_16x16x32_bf16 v[36:39], v[228:231], v[240:243], v[36:39]
	v_mfma_f32_16x16x32_bf16 v[32:35], v[232:235], v[240:243], v[32:35]
	s_waitcnt lgkmcnt(1)
	v_mfma_f32_16x16x32_bf16 v[28:31], v[220:223], v[244:247], v[28:31]
	v_mfma_f32_16x16x32_bf16 v[24:27], v[224:227], v[244:247], v[24:27]
	v_mfma_f32_16x16x32_bf16 v[20:23], v[228:231], v[244:247], v[20:23]
	v_mfma_f32_16x16x32_bf16 v[16:19], v[232:235], v[244:247], v[16:19]
	s_waitcnt lgkmcnt(0)
	v_mfma_f32_16x16x32_bf16 v[12:15], v[220:223], v[248:251], v[12:15]
	v_mfma_f32_16x16x32_bf16 v[8:11], v[224:227], v[248:251], v[8:11]
	v_mfma_f32_16x16x32_bf16 v[4:7], v[228:231], v[248:251], v[4:7]
	v_mfma_f32_16x16x32_bf16 v[0:3], v[232:235], v[248:251], v[0:3]
	s_setprio 0
	s_waitcnt vmcnt(1)
	ds_write_b128 v168, v[184:187]
	ds_write_b128 v168, v[200:203] offset:4096
	ds_write_b128 v168, v[204:207] offset:8192
	ds_write_b128 v168, v[208:211] offset:12288
	ds_write_b128 v169, v[212:215] offset:32768
	ds_write_b128 v169, v[216:219] offset:36864
	s_waitcnt lgkmcnt(0)
	s_add_i32 s15, s15, 64
	s_mov_b32 s17, s27
	s_barrier
	s_cbranch_vccnz .LBB0_110
	s_waitcnt vmcnt(0)
	s_cmpk_gt_i32 s26, 0xcff
	s_mov_b64 s[0:1], -1
	s_cbranch_scc0 .LBB0_115
	v_or_b32_e32 v128, v161, v163
	v_cmp_eq_u32_e32 vcc, 0, v128
	s_and_saveexec_b64 s[0:1], vcc
	s_cbranch_execz .LBB0_114
	v_and_b32_e32 v128, 0xffffff80, v198
	v_add_u32_e32 v128, s16, v128
	v_or_b32_e32 v128, v128, v171
	v_ashrrev_i32_e32 v129, 31, v128
	v_lshlrev_b64 v[130:131], 6, v[128:129]
	v_lshl_add_u64 v[130:131], s[62:63], 0, v[130:131]
	global_store_dwordx4 v[130:131], v[124:127], off
	global_store_dwordx4 v[130:131], v[120:123], off offset:16
	global_store_dwordx4 v[130:131], v[116:119], off offset:32
	global_store_dwordx4 v[130:131], v[112:115], off offset:48
	v_or_b32_e32 v130, 16, v128
	v_ashrrev_i32_e32 v131, 31, v130
	v_lshlrev_b64 v[130:131], 6, v[130:131]
	v_lshl_add_u64 v[130:131], s[62:63], 0, v[130:131]
	global_store_dwordx4 v[130:131], v[108:111], off
	global_store_dwordx4 v[130:131], v[104:107], off offset:16
	global_store_dwordx4 v[130:131], v[100:103], off offset:32
	global_store_dwordx4 v[130:131], v[96:99], off offset:48
	v_or_b32_e32 v130, 32, v128
	v_ashrrev_i32_e32 v131, 31, v130
	v_lshlrev_b64 v[130:131], 6, v[130:131]
	v_lshl_add_u64 v[130:131], s[62:63], 0, v[130:131]
	global_store_dwordx4 v[130:131], v[92:95], off
	global_store_dwordx4 v[130:131], v[88:91], off offset:16
	global_store_dwordx4 v[130:131], v[84:87], off offset:32
	global_store_dwordx4 v[130:131], v[80:83], off offset:48
	v_or_b32_e32 v130, 48, v128
	v_ashrrev_i32_e32 v131, 31, v130
	v_lshlrev_b64 v[130:131], 6, v[130:131]
	v_lshl_add_u64 v[130:131], s[62:63], 0, v[130:131]
	global_store_dwordx4 v[130:131], v[76:79], off
	global_store_dwordx4 v[130:131], v[72:75], off offset:16
	global_store_dwordx4 v[130:131], v[68:71], off offset:32
	global_store_dwordx4 v[130:131], v[64:67], off offset:48
	v_or_b32_e32 v130, 64, v128
	v_ashrrev_i32_e32 v131, 31, v130
	v_lshlrev_b64 v[130:131], 6, v[130:131]
	v_lshl_add_u64 v[130:131], s[62:63], 0, v[130:131]
	global_store_dwordx4 v[130:131], v[60:63], off
	global_store_dwordx4 v[130:131], v[56:59], off offset:16
	global_store_dwordx4 v[130:131], v[52:55], off offset:32
	global_store_dwordx4 v[130:131], v[48:51], off offset:48
	v_or_b32_e32 v130, 0x50, v128
	v_ashrrev_i32_e32 v131, 31, v130
	v_lshlrev_b64 v[130:131], 6, v[130:131]
	v_lshl_add_u64 v[130:131], s[62:63], 0, v[130:131]
	global_store_dwordx4 v[130:131], v[44:47], off
	global_store_dwordx4 v[130:131], v[40:43], off offset:16
	global_store_dwordx4 v[130:131], v[36:39], off offset:32
	global_store_dwordx4 v[130:131], v[32:35], off offset:48
	v_or_b32_e32 v130, 0x60, v128
	v_or_b32_e32 v128, 0x70, v128
	v_ashrrev_i32_e32 v131, 31, v130
	v_ashrrev_i32_e32 v129, 31, v128
	v_lshlrev_b64 v[130:131], 6, v[130:131]
	v_lshlrev_b64 v[128:129], 6, v[128:129]
	v_lshl_add_u64 v[130:131], s[62:63], 0, v[130:131]
	v_lshl_add_u64 v[128:129], s[62:63], 0, v[128:129]
	global_store_dwordx4 v[130:131], v[28:31], off
	global_store_dwordx4 v[130:131], v[24:27], off offset:16
	global_store_dwordx4 v[130:131], v[20:23], off offset:32
	global_store_dwordx4 v[130:131], v[16:19], off offset:48
	global_store_dwordx4 v[128:129], v[12:15], off
	global_store_dwordx4 v[128:129], v[8:11], off offset:16
	global_store_dwordx4 v[128:129], v[4:7], off offset:32
	global_store_dwordx4 v[128:129], v[0:3], off offset:48

; #define MFMA16(a, b, c) __builtin_amdgcn_mfma_f32_16x16x32_bf16((a), (b), (c), 0, 0, 0)
; __device__ __forceinline__ bf16x8 gld16(const void* p) { bf16x8 v; asm volatile("global_load_dwordx4 %0, %1, off" : "=v"(v) : "v"(p) : "memory"); return v; }
; template <bool SWAP>
; __device__ __forceinline__ void gemm_big(const bfu* __restrict__ A, int lda, const bfu* __restrict__ B, int ldb, int K,
;                                          f32x4 (&acc)[8][4], bfu* sm, const bfu* An = nullptr, const bfu* Bn = nullptr) {
;     ...
;   auto gl = [&](bf16x8 (&ra)[4], bf16x8 (&rb)[2], int kt) {
;     const bool nx = (kt >= nk);
;     const bfu* pa = nx ? (chain ? Apn + (kt - nk) * 32 : Ap + (nk - 1) * 32) : Ap + kt * 32;
;     const bfu* pb = nx ? (chain ? Bpn + (kt - nk) * 32 : Bp + (nk - 1) * 32) : Bp + kt * 32;
; #pragma unroll
;     for (int q = 0; q < 4; ++q) ra[q] = gld16(pa + (size_t)(64 * q) * lda);
; #pragma unroll
;     for (int q = 0; q < 2; ++q) rb[q] = gld16(pb + (size_t)(64 * q) * ldb);
;   };
;   auto wt = [&](bf16x8 (&ra)[4], bf16x8 (&rb)[2]) {
;     asm volatile("s_waitcnt vmcnt(6)" : "+v"(ra[0]), "+v"(ra[1]), "+v"(ra[2]), "+v"(ra[3]), "+v"(rb[0]), "+v"(rb[1]) : : "memory");
;   };
;   auto st = [&](const bf16x8 (&ra)[4], const bf16x8 (&rb)[2], int buf) {
; #pragma unroll
;     for (int q = 0; q < 4; ++q) *(bf16x8*)(As + (buf * 256 + lrow + 64 * q) * 40 + lch) = ra[q];
; #pragma unroll
;     for (int q = 0; q < 2; ++q) *(bf16x8*)(Bs + (buf * 128 + brow + 64 * q) * 40 + lch) = rb[q];
;   };
;   auto comp = [&](int buf, auto&& mid) {
;     const bfu* as = As + buf * 256 * 40 + (wr * 128 + c15) * 40 + g * 8;
;     const bfu* bs = Bs + buf * 128 * 40 + (wc * 64 + c15) * 40 + g * 8;
;     bf16x8 b[4];
; #pragma unroll
;     for (int j = 0; j < 4; ++j) b[j] = *(const bf16x8*)(bs + j * 16 * 40);
;     {
;       bf16x8 a[4];
; #pragma unroll
;       for (int i = 0; i < 4; ++i) a[i] = *(const bf16x8*)(as + i * 16 * 40);
;       mid();
;       __builtin_amdgcn_s_setprio(1);
; #pragma unroll
;       for (int i = 0; i < 4; ++i)
; #pragma unroll
;         for (int j = 0; j < 4; ++j) acc[i][j] = SWAP ? MFMA16(b[j], a[i], acc[i][j]) : MFMA16(a[i], b[j], acc[i][j]);
;       __builtin_amdgcn_s_setprio(0);
;     }
;     ...
;   for (int kt = 0; kt < nk; kt += 2) {
;     gl(ra0, rb0, kt + 2);
;     comp(0, [&]() { wt(ra1, rb1); st(ra1, rb1, 1); });
;     __syncthreads();
.LBB0_132:
	s_add_i32 s18, s17, 2
	s_cmp_lt_u32 s17, 30
	s_cselect_b64 s[0:1], -1, 0
	s_add_i32 s2, s15, 0x400
	s_and_b64 s[20:21], s[10:11], exec
	s_cselect_b32 s19, 0x3e0, s15
	s_and_b64 vcc, s[0:1], exec
	s_cselect_b32 s2, s2, s19
	v_cndmask_b32_e64 v201, v157, v165, s[0:1]
	v_cndmask_b32_e64 v200, v152, v164, s[0:1]
	v_cndmask_b32_e64 v203, v159, v167, s[0:1]
	v_cndmask_b32_e64 v202, v170, v166, s[0:1]
	s_lshl_b64 s[0:1], s[2:3], 1
	v_lshl_add_u64 v[212:213], v[200:201], 0, s[0:1]
	v_lshl_add_u64 v[220:221], v[202:203], 0, s[0:1]
	ds_read_b128 v[224:227], v169 offset:32768
	ds_read_b128 v[228:231], v169 offset:33792
	ds_read_b128 v[232:235], v169 offset:34816
	ds_read_b128 v[236:239], v169 offset:35840
	ds_read_b128 v[240:243], v172
	ds_read_b128 v[244:247], v172 offset:1024
	ds_read_b128 v[248:251], v172 offset:2048
	ds_read_b128 v[184:187], v172 offset:3072
	s_waitcnt vmcnt(0)
	ds_write_b128 v168, v[48:51] offset:16384
	ds_write_b128 v168, v[56:59] offset:20480
	ds_write_b128 v168, v[60:63] offset:24576
	ds_write_b128 v168, v[68:71] offset:28672
	ds_write_b128 v168, v[72:75] offset:40960
	ds_write_b128 v168, v[80:83] offset:45056
	s_cmp_lt_u32 s17, 29
	s_cselect_b64 s[0:1], -1, 0
	s_add_i32 s2, s15, 0x420
	s_add_i32 s17, s15, 32
	s_and_b64 s[20:21], s[10:11], exec
	s_cselect_b32 s17, 0x3e0, s17
	s_and_b64 s[20:21], s[0:1], exec
	s_cselect_b32 s2, s2, s17
	v_cndmask_b32_e64 v49, v157, v165, s[0:1]
	v_cndmask_b32_e64 v48, v152, v164, s[0:1]
	v_cndmask_b32_e64 v51, v159, v167, s[0:1]
	v_cndmask_b32_e64 v50, v170, v166, s[0:1]
	s_lshl_b64 s[0:1], s[2:3], 1
	v_lshl_add_u64 v[68:69], v[48:49], 0, s[0:1]
	v_lshl_add_u64 v[80:81], v[50:51], 0, s[0:1]
	s_setprio 1
	s_waitcnt lgkmcnt(9)
	v_mfma_f32_16x16x32_bf16 v[148:151], v[240:243], v[224:227], v[148:151]
	global_load_dwordx4 v[200:203], v[212:213], off
	v_mfma_f32_16x16x32_bf16 v[144:147], v[240:243], v[228:231], v[144:147]
	global_load_dwordx4 v[48:51], v[68:69], off
	v_mfma_f32_16x16x32_bf16 v[140:143], v[240:243], v[232:235], v[140:143]
	v_lshl_add_u64 v[204:205], v[212:213], 0, s[8:9]
	global_load_dwordx4 v[204:207], v[204:205], off
	v_mfma_f32_16x16x32_bf16 v[136:139], v[240:243], v[236:239], v[136:139]
	v_lshl_add_u64 v[56:57], v[68:69], 0, s[8:9]
	global_load_dwordx4 v[56:59], v[56:57], off
	s_waitcnt lgkmcnt(8)
	v_mfma_f32_16x16x32_bf16 v[132:135], v[244:247], v[224:227], v[132:135]
	v_lshl_add_u64 v[208:209], v[212:213], 0, s[4:5]
	global_load_dwordx4 v[208:211], v[208:209], off
	v_mfma_f32_16x16x32_bf16 v[128:131], v[244:247], v[228:231], v[128:131]
	v_lshl_add_u64 v[60:61], v[68:69], 0, s[4:5]
	global_load_dwordx4 v[60:63], v[60:61], off
	v_mfma_f32_16x16x32_bf16 v[124:127], v[244:247], v[232:235], v[124:127]
	v_lshl_add_u64 v[212:213], v[212:213], 0, s[90:91]
	global_load_dwordx4 v[212:215], v[212:213], off
	v_mfma_f32_16x16x32_bf16 v[120:123], v[244:247], v[236:239], v[120:123]
	v_lshl_add_u64 v[68:69], v[68:69], 0, s[90:91]
	global_load_dwordx4 v[68:71], v[68:69], off
	s_waitcnt lgkmcnt(7)
	v_mfma_f32_16x16x32_bf16 v[116:119], v[248:251], v[224:227], v[116:119]
	global_load_dwordx4 v[216:219], v[220:221], off
	v_mfma_f32_16x16x32_bf16 v[112:115], v[248:251], v[228:231], v[112:115]
	global_load_dwordx4 v[72:75], v[80:81], off
	v_mfma_f32_16x16x32_bf16 v[108:111], v[248:251], v[232:235], v[108:111]
	v_lshl_add_u64 v[220:221], v[220:221], 0, s[8:9]
	global_load_dwordx4 v[220:223], v[220:221], off
	v_mfma_f32_16x16x32_bf16 v[104:107], v[248:251], v[236:239], v[104:107]
	v_lshl_add_u64 v[80:81], v[80:81], 0, s[8:9]
	global_load_dwordx4 v[80:83], v[80:81], off
	s_waitcnt lgkmcnt(6)
	v_mfma_f32_16x16x32_bf16 v[100:103], v[184:187], v[224:227], v[100:103]
	v_mfma_f32_16x16x32_bf16 v[96:99], v[184:187], v[228:231], v[96:99]
	v_mfma_f32_16x16x32_bf16 v[92:95], v[184:187], v[232:235], v[92:95]
	v_mfma_f32_16x16x32_bf16 v[88:91], v[184:187], v[236:239], v[88:91]
	s_setprio 0
	ds_read_b128 v[240:243], v172 offset:4096
	ds_read_b128 v[244:247], v172 offset:5120
	ds_read_b128 v[248:251], v172 offset:6144
	ds_read_b128 v[184:187], v172 offset:7168
	s_setprio 1
	s_waitcnt lgkmcnt(3)
	v_mfma_f32_16x16x32_bf16 v[84:87], v[240:243], v[224:227], v[84:87]
	v_mfma_f32_16x16x32_bf16 v[76:79], v[240:243], v[228:231], v[76:79]
	v_mfma_f32_16x16x32_bf16 v[64:67], v[240:243], v[232:235], v[64:67]
	v_mfma_f32_16x16x32_bf16 v[52:55], v[240:243], v[236:239], v[52:55]
	s_waitcnt lgkmcnt(2)
	v_mfma_f32_16x16x32_bf16 v[44:47], v[244:247], v[224:227], v[44:47]
	v_mfma_f32_16x16x32_bf16 v[40:43], v[244:247], v[228:231], v[40:43]
	v_mfma_f32_16x16x32_bf16 v[36:39], v[244:247], v[232:235], v[36:39]
	v_mfma_f32_16x16x32_bf16 v[32:35], v[244:247], v[236:239], v[32:35]
	s_waitcnt lgkmcnt(1)
	v_mfma_f32_16x16x32_bf16 v[28:31], v[248:251], v[224:227], v[28:31]
	v_mfma_f32_16x16x32_bf16 v[24:27], v[248:251], v[228:231], v[24:27]
	v_mfma_f32_16x16x32_bf16 v[20:23], v[248:251], v[232:235], v[20:23]
	v_mfma_f32_16x16x32_bf16 v[16:19], v[248:251], v[236:239], v[16:19]
	s_waitcnt lgkmcnt(0)
	v_mfma_f32_16x16x32_bf16 v[12:15], v[184:187], v[224:227], v[12:15]
	v_mfma_f32_16x16x32_bf16 v[8:11], v[184:187], v[228:231], v[8:11]
	v_mfma_f32_16x16x32_bf16 v[4:7], v[184:187], v[232:235], v[4:7]
	v_mfma_f32_16x16x32_bf16 v[0:3], v[184:187], v[236:239], v[0:3]
	s_setprio 0
	s_barrier
; #define MFMA16(a, b, c) __builtin_amdgcn_mfma_f32_16x16x32_bf16((a), (b), (c), 0, 0, 0)
;   __device__ __forceinline__ float* gl() const { return (float*)(b + L::o_gl); }
; template <bool SWAP>
; __device__ __forceinline__ void gemm_big(const bfu* __restrict__ A, int lda, const bfu* __restrict__ B, int ldb, int K,
;                                          f32x4 (&acc)[8][4], bfu* sm, const bfu* An = nullptr, const bfu* Bn = nullptr) {
;     ...
;     {
;       bf16x8 a[4];
; #pragma unroll
;       for (int i = 0; i < 4; ++i) a[i] = *(const bf16x8*)(as + (i + 4) * 16 * 40);
;       __builtin_amdgcn_s_setprio(1);
; #pragma unroll
;       for (int i = 0; i < 4; ++i)
; #pragma unroll
;         for (int j = 0; j < 4; ++j) acc[i + 4][j] = SWAP ? MFMA16(b[j], a[i], acc[i + 4][j]) : MFMA16(a[i], b[j], acc[i + 4][j]);
;       __builtin_amdgcn_s_setprio(0);
;     }
;   };
;     ...
;     gl(ra1, rb1, kt + 3);
;     comp(1, [&]() { wt(ra0, rb0); st(ra0, rb0, 0); });
;     __syncthreads();
;   }
	ds_read_b128 v[184:187], v169 offset:40960
	ds_read_b128 v[224:227], v169 offset:41984
	ds_read_b128 v[228:231], v169 offset:43008
	ds_read_b128 v[232:235], v169 offset:44032
	ds_read_b128 v[236:239], v172 offset:16384
	ds_read_b128 v[240:243], v172 offset:17408
	ds_read_b128 v[244:247], v172 offset:18432
	ds_read_b128 v[248:251], v172 offset:19456
	s_setprio 1
	s_waitcnt lgkmcnt(3)
	v_mfma_f32_16x16x32_bf16 v[148:151], v[236:239], v[184:187], v[148:151]
	v_mfma_f32_16x16x32_bf16 v[144:147], v[236:239], v[224:227], v[144:147]
	v_mfma_f32_16x16x32_bf16 v[140:143], v[236:239], v[228:231], v[140:143]
	v_mfma_f32_16x16x32_bf16 v[136:139], v[236:239], v[232:235], v[136:139]
	s_waitcnt lgkmcnt(2)
	v_mfma_f32_16x16x32_bf16 v[132:135], v[240:243], v[184:187], v[132:135]
	v_mfma_f32_16x16x32_bf16 v[128:131], v[240:243], v[224:227], v[128:131]
	v_mfma_f32_16x16x32_bf16 v[124:127], v[240:243], v[228:231], v[124:127]
	v_mfma_f32_16x16x32_bf16 v[120:123], v[240:243], v[232:235], v[120:123]
	s_waitcnt lgkmcnt(1)
	v_mfma_f32_16x16x32_bf16 v[116:119], v[244:247], v[184:187], v[116:119]
	v_mfma_f32_16x16x32_bf16 v[112:115], v[244:247], v[224:227], v[112:115]
	v_mfma_f32_16x16x32_bf16 v[108:111], v[244:247], v[228:231], v[108:111]
	v_mfma_f32_16x16x32_bf16 v[104:107], v[244:247], v[232:235], v[104:107]
	s_waitcnt lgkmcnt(0)
	v_mfma_f32_16x16x32_bf16 v[100:103], v[248:251], v[184:187], v[100:103]
	v_mfma_f32_16x16x32_bf16 v[96:99], v[248:251], v[224:227], v[96:99]
	v_mfma_f32_16x16x32_bf16 v[92:95], v[248:251], v[228:231], v[92:95]
	v_mfma_f32_16x16x32_bf16 v[88:91], v[248:251], v[232:235], v[88:91]
	s_setprio 0
	ds_read_b128 v[236:239], v172 offset:20480
	ds_read_b128 v[240:243], v172 offset:21504
	ds_read_b128 v[244:247], v172 offset:22528
	ds_read_b128 v[248:251], v172 offset:23552
	s_setprio 1
	s_waitcnt lgkmcnt(3)
	v_mfma_f32_16x16x32_bf16 v[84:87], v[236:239], v[184:187], v[84:87]
	v_mfma_f32_16x16x32_bf16 v[76:79], v[236:239], v[224:227], v[76:79]
	v_mfma_f32_16x16x32_bf16 v[64:67], v[236:239], v[228:231], v[64:67]
	v_mfma_f32_16x16x32_bf16 v[52:55], v[236:239], v[232:235], v[52:55]
	s_waitcnt lgkmcnt(2)
	v_mfma_f32_16x16x32_bf16 v[44:47], v[240:243], v[184:187], v[44:47]
	v_mfma_f32_16x16x32_bf16 v[40:43], v[240:243], v[224:227], v[40:43]
	v_mfma_f32_16x16x32_bf16 v[36:39], v[240:243], v[228:231], v[36:39]
	v_mfma_f32_16x16x32_bf16 v[32:35], v[240:243], v[232:235], v[32:35]
	s_waitcnt lgkmcnt(1)
	v_mfma_f32_16x16x32_bf16 v[28:31], v[244:247], v[184:187], v[28:31]
	v_mfma_f32_16x16x32_bf16 v[24:27], v[244:247], v[224:227], v[24:27]
	v_mfma_f32_16x16x32_bf16 v[20:23], v[244:247], v[228:231], v[20:23]
	v_mfma_f32_16x16x32_bf16 v[16:19], v[244:247], v[232:235], v[16:19]
	s_waitcnt lgkmcnt(0)
	v_mfma_f32_16x16x32_bf16 v[12:15], v[248:251], v[184:187], v[12:15]
	v_mfma_f32_16x16x32_bf16 v[8:11], v[248:251], v[224:227], v[8:11]
	v_mfma_f32_16x16x32_bf16 v[4:7], v[248:251], v[228:231], v[4:7]
	v_mfma_f32_16x16x32_bf16 v[0:3], v[248:251], v[232:235], v[0:3]
	s_setprio 0
	s_waitcnt vmcnt(1)
	ds_write_b128 v168, v[200:203]
	ds_write_b128 v168, v[204:207] offset:4096
	ds_write_b128 v168, v[208:211] offset:8192
	ds_write_b128 v168, v[212:215] offset:12288
	ds_write_b128 v168, v[216:219] offset:32768
	ds_write_b128 v168, v[220:223] offset:36864
	s_waitcnt lgkmcnt(0)
	s_add_i32 s15, s15, 64
	s_mov_b32 s17, s18
	s_barrier
	s_cbranch_vccnz .LBB0_132
;   __device__ __forceinline__ bfu* VtC() const { return (bfu*)(b + L::o_VtC); }
;   __device__ __forceinline__ bfu* VtD() const { return (bfu*)(b + L::o_VtD); }
;   __device__ __forceinline__ bfu* rb() const { return (bfu*)(b + L::o_rb); }
; template <int G>
; __device__ __forceinline__ void p1_big(const Params& P, const Ptrs<G>& w, int layer, int mt, int nt, bfu* sm, int mtn, int ntn) {
;     ...
;     bfu* dst = (n0 < 7168) ? w.VtC() : w.VtD();
;     const int cofs = (n0 < 7168) ? (n0 - 6656) : (n0 - 7168);
; #pragma unroll
;     for (int i = 0; i < 8; ++i)
; #pragma unroll
;       for (int j = 0; j < 4; ++j) {
;         int rb = m0 + wr * 128 + i * 16 + g * 4; int c = cofs + wc * 64 + j * 16 + c15;
;         int seq = rb >> 13, t = rb & 8191, h = c >> 6, d = c & 63;
;         uint2 o; o.x = pack2(acc[i][j][0], acc[i][j][1]); o.y = pack2(acc[i][j][2], acc[i][j][3]);
;         *(uint2*)(dst + ((size_t)((seq * 8 + h) * 64 + d)) * TSEQ + t) = o;
;       }
	s_cmp_lt_u32 s35, 56
	s_cselect_b64 s[0:1], -1, 0
	s_waitcnt vmcnt(0)
	s_and_b64 s[0:1], s[0:1], exec
	s_movk_i32 s0, 0xe600
	v_and_b32_e32 v48, 0xffffff80, v198
	s_cselect_b32 s2, s0, 0xffffe400
	v_add_u32_e32 v48, s16, v48
	v_or_b32_e32 v50, s14, v171
	s_mov_b32 s0, 0x18121800
	v_readlane_b32 s20, v253, 38
	v_and_b32_e32 v49, 0x1f80, v48
	v_ashrrev_i32_e32 v48, 4, v48
	v_add_u32_e32 v50, s2, v50
	s_cselect_b32 s0, s0, 0x19121800
	v_readlane_b32 s22, v253, 40
	v_and_b32_e32 v48, 0xfffffe00, v48
	v_lshl_or_b32 v50, v161, 6, v50
	v_readlane_b32 s23, v253, 41
	s_add_u32 s0, s22, s0
	v_add_u32_e32 v48, v50, v48
	v_lshlrev_b32_e32 v49, 1, v49
	s_addc_u32 s1, s23, 0
	v_lshl_or_b32 v152, v163, 3, v49
	v_ashrrev_i32_e32 v49, 31, v48
	v_lshl_add_u64 v[50:51], s[0:1], 0, v[152:153]
	v_lshlrev_b64 v[56:57], 14, v[48:49]
	v_lshl_add_u64 v[56:57], v[50:51], 0, v[56:57]
	v_cvt_pk_bf16_f32 v59, v150, v151
	v_cvt_pk_bf16_f32 v58, v148, v149
	global_store_dwordx2 v[56:57], v[58:59], off
	v_or_b32_e32 v58, 16, v48
	v_ashrrev_i32_e32 v59, 31, v58
	v_lshlrev_b64 v[58:59], 14, v[58:59]
	v_lshl_add_u64 v[58:59], v[50:51], 0, v[58:59]
	v_cvt_pk_bf16_f32 v61, v146, v147
	v_cvt_pk_bf16_f32 v60, v144, v145
	global_store_dwordx2 v[58:59], v[60:61], off
	v_or_b32_e32 v60, 32, v48
	v_or_b32_e32 v48, 48, v48
	v_ashrrev_i32_e32 v61, 31, v60
	v_ashrrev_i32_e32 v49, 31, v48
	v_lshlrev_b64 v[60:61], 14, v[60:61]
	v_lshlrev_b64 v[48:49], 14, v[48:49]
	v_lshl_add_u64 v[60:61], v[50:51], 0, v[60:61]
	v_lshl_add_u64 v[48:49], v[50:51], 0, v[48:49]
	v_cvt_pk_bf16_f32 v51, v138, v139
	v_cvt_pk_bf16_f32 v50, v136, v137
	global_store_dwordx2 v[48:49], v[50:51], off
	v_cvt_pk_bf16_f32 v51, v134, v135
	v_cvt_pk_bf16_f32 v50, v132, v133
	global_store_dwordx2 v[56:57], v[50:51], off offset:32
	v_cvt_pk_bf16_f32 v51, v130, v131
	v_cvt_pk_bf16_f32 v50, v128, v129
	global_store_dwordx2 v[58:59], v[50:51], off offset:32
	v_cvt_pk_bf16_f32 v51, v126, v127
	v_cvt_pk_bf16_f32 v50, v124, v125
	global_store_dwordx2 v[60:61], v[50:51], off offset:32
	v_cvt_pk_bf16_f32 v51, v122, v123
	v_cvt_pk_bf16_f32 v50, v120, v121
	global_store_dwordx2 v[48:49], v[50:51], off offset:32
	v_cvt_pk_bf16_f32 v51, v118, v119
	v_cvt_pk_bf16_f32 v50, v116, v117
	global_store_dwordx2 v[56:57], v[50:51], off offset:64
	v_cvt_pk_bf16_f32 v51, v114, v115
	v_cvt_pk_bf16_f32 v50, v112, v113
	global_store_dwordx2 v[58:59], v[50:51], off offset:64
	v_cvt_pk_bf16_f32 v51, v110, v111
	v_cvt_pk_bf16_f32 v50, v108, v109
	global_store_dwordx2 v[60:61], v[50:51], off offset:64
	v_cvt_pk_bf16_f32 v51, v106, v107
	v_cvt_pk_bf16_f32 v50, v104, v105
	global_store_dwordx2 v[48:49], v[50:51], off offset:64
	v_cvt_pk_bf16_f32 v51, v102, v103
	v_cvt_pk_bf16_f32 v50, v100, v101
	global_store_dwordx2 v[56:57], v[50:51], off offset:96
	v_cvt_pk_bf16_f32 v51, v98, v99
	v_cvt_pk_bf16_f32 v50, v96, v97
	global_store_dwordx2 v[58:59], v[50:51], off offset:96
	v_cvt_pk_bf16_f32 v51, v94, v95
	v_cvt_pk_bf16_f32 v50, v92, v93
	global_store_dwordx2 v[60:61], v[50:51], off offset:96
	v_cvt_pk_bf16_f32 v51, v90, v91
	v_cvt_pk_bf16_f32 v50, v88, v89
	global_store_dwordx2 v[48:49], v[50:51], off offset:96
	v_cvt_pk_bf16_f32 v51, v86, v87
	v_cvt_pk_bf16_f32 v50, v84, v85
	global_store_dwordx2 v[56:57], v[50:51], off offset:128
	v_cvt_pk_bf16_f32 v51, v78, v79
	v_cvt_pk_bf16_f32 v50, v76, v77
	global_store_dwordx2 v[58:59], v[50:51], off offset:128
	v_cvt_pk_bf16_f32 v51, v66, v67
	v_cvt_pk_bf16_f32 v50, v64, v65
	v_cvt_pk_bf16_f32 v63, v142, v143
	v_cvt_pk_bf16_f32 v62, v140, v141
	global_store_dwordx2 v[60:61], v[50:51], off offset:128
	v_cvt_pk_bf16_f32 v51, v54, v55
	v_cvt_pk_bf16_f32 v50, v52, v53
	v_cvt_pk_bf16_f32 v47, v46, v47
	v_cvt_pk_bf16_f32 v46, v44, v45
	v_cvt_pk_bf16_f32 v43, v42, v43
	v_cvt_pk_bf16_f32 v42, v40, v41
	v_cvt_pk_bf16_f32 v39, v38, v39
	v_cvt_pk_bf16_f32 v38, v36, v37
	v_cvt_pk_bf16_f32 v35, v34, v35
	v_cvt_pk_bf16_f32 v34, v32, v33
	v_cvt_pk_bf16_f32 v31, v30, v31
	v_cvt_pk_bf16_f32 v30, v28, v29
	v_cvt_pk_bf16_f32 v27, v26, v27
	v_cvt_pk_bf16_f32 v26, v24, v25
	v_cvt_pk_bf16_f32 v23, v22, v23
	v_cvt_pk_bf16_f32 v22, v20, v21
	v_cvt_pk_bf16_f32 v19, v18, v19
	v_cvt_pk_bf16_f32 v18, v16, v17
	v_cvt_pk_bf16_f32 v15, v14, v15
	v_cvt_pk_bf16_f32 v14, v12, v13
	v_cvt_pk_bf16_f32 v11, v10, v11
	v_cvt_pk_bf16_f32 v10, v8, v9
	v_cvt_pk_bf16_f32 v7, v6, v7
	v_cvt_pk_bf16_f32 v6, v4, v5
	v_cvt_pk_bf16_f32 v3, v2, v3
	v_cvt_pk_bf16_f32 v2, v0, v1
	v_readlane_b32 s21, v253, 39
	global_store_dwordx2 v[60:61], v[62:63], off
	global_store_dwordx2 v[48:49], v[50:51], off offset:128
	global_store_dwordx2 v[56:57], v[46:47], off offset:160
	global_store_dwordx2 v[58:59], v[42:43], off offset:160
	global_store_dwordx2 v[60:61], v[38:39], off offset:160
	global_store_dwordx2 v[48:49], v[34:35], off offset:160
	global_store_dwordx2 v[56:57], v[30:31], off offset:192
	global_store_dwordx2 v[58:59], v[26:27], off offset:192
	global_store_dwordx2 v[60:61], v[22:23], off offset:192
	global_store_dwordx2 v[48:49], v[18:19], off offset:192
	global_store_dwordx2 v[56:57], v[14:15], off offset:224
	global_store_dwordx2 v[58:59], v[10:11], off offset:224
	global_store_dwordx2 v[60:61], v[6:7], off offset:224
	global_store_dwordx2 v[48:49], v[2:3], off offset:224
	s_branch .LBB0_106
